# row sum-of-squares ds_bpermute chains -> DPP + permlane swaps at 6 sites (adds the phase0 first-norm site)
# speedup vs baseline: 1.0070x; 1.0070x over previous
.LBB0_363:
	v_and_b32_e32 v64, 0x1ff, v137
	v_mov_b32_e32 v66, v139
	v_mov_b32_e32 v67, v139
	v_cmp_gt_i32_e32 vcc, s15, v137
	v_cmp_ne_u32_e64 s[0:1], 0, v64
	v_mov_b32_e32 v64, v139
	v_mov_b32_e32 v65, v139
	v_mov_b64_e32 v[70:71], v[66:67]
	v_mov_b64_e32 v[90:91], v[66:67]
	v_mov_b64_e32 v[98:99], v[66:67]
	v_lshlrev_b32_e32 v72, 3, v137
	s_and_b64 s[16:17], vcc, s[0:1]
	v_lshlrev_b32_e32 v138, 2, v136
	v_mov_b64_e32 v[68:69], v[64:65]
	v_mov_b64_e32 v[88:89], v[64:65]
	v_mov_b64_e32 v[96:97], v[64:65]
	s_and_saveexec_b64 s[0:1], s[16:17]
	s_cbranch_execz .LBB0_365
	v_add_u32_e32 v82, -1, v72
	v_ashrrev_i32_e32 v83, 31, v82
	v_lshlrev_b64 v[64:65], 12, v[82:83]
	v_lshl_add_u64 v[78:79], v[140:141], 0, v[64:65]
	global_load_dwordx4 v[64:67], v[78:79], off
	global_load_dwordx4 v[68:71], v[78:79], off offset:1024
	global_load_dwordx4 v[74:77], v[78:79], off offset:3072
	s_nop 0
	global_load_dwordx4 v[78:81], v[78:79], off offset:2048
	v_ashrrev_i32_e32 v73, 12, v82
	v_mul_hi_i32_i24_e32 v83, 0x6000, v73
	v_mul_i32_i24_e32 v82, 0x6000, v73
	v_lshl_add_u64 v[98:99], s[76:77], 0, v[82:83]
	v_lshl_add_u64 v[94:95], v[98:99], 0, s[12:13]
	v_mov_b32_e32 v155, v139
	v_lshl_add_u64 v[90:91], v[94:95], 0, v[154:155]
	global_load_dwordx4 v[90:93], v[90:91], off
	v_mov_b32_e32 v153, v139
	v_mov_b32_e32 v157, v139
	v_lshl_add_u64 v[82:83], v[94:95], 0, v[138:139]
	v_lshl_add_u64 v[86:87], v[94:95], 0, v[152:153]
	v_lshl_add_u64 v[94:95], v[94:95], 0, v[156:157]
	global_load_dwordx4 v[82:85], v[82:83], off
	v_lshl_add_u64 v[98:99], v[98:99], 0, v[138:139]
	global_load_dwordx4 v[86:89], v[86:87], off
	s_waitcnt vmcnt(6)
	v_mov_b32_e32 v116, v65
	global_load_dwordx4 v[94:97], v[94:95], off
	s_nop 0
	global_load_dwordx4 v[100:103], v[98:99], off
	global_load_dwordx4 v[104:107], v[98:99], off offset:1024
	global_load_dwordx4 v[108:111], v[98:99], off offset:2048
	global_load_dwordx4 v[112:115], v[98:99], off offset:3072
	s_waitcnt vmcnt(10)
	v_mov_b32_e32 v117, v69
	v_mov_b32_e32 v98, v64
	v_mov_b32_e32 v99, v68
	s_waitcnt vmcnt(9)
	v_mov_b32_e32 v124, v75
	s_waitcnt vmcnt(8)
	v_mov_b32_e32 v125, v79
	v_pk_mul_f32 v[116:117], v[116:117], v[116:117]
	v_mov_b32_e32 v118, v66
	v_mov_b32_e32 v119, v70
	v_mov_b32_e32 v122, v74
	v_mov_b32_e32 v123, v78
	v_pk_mul_f32 v[124:125], v[124:125], v[124:125]
	v_pk_fma_f32 v[98:99], v[98:99], v[98:99], v[116:117]
	v_mov_b32_e32 v120, v67
	v_mov_b32_e32 v121, v71
	v_mov_b32_e32 v126, v76
	v_mov_b32_e32 v127, v80
	v_pk_fma_f32 v[116:117], v[122:123], v[122:123], v[124:125]
	v_pk_fma_f32 v[98:99], v[118:119], v[118:119], v[98:99]
	v_mov_b32_e32 v128, v77
	v_mov_b32_e32 v129, v81
	v_pk_fma_f32 v[116:117], v[126:127], v[126:127], v[116:117]
	v_pk_fma_f32 v[98:99], v[120:121], v[120:121], v[98:99]
	v_pk_fma_f32 v[116:117], v[128:129], v[128:129], v[116:117]
	v_add_f32_e32 v73, v98, v99
	v_add_f32_e32 v73, v117, v73
	v_add_f32_e32 v73, v116, v73
	s_waitcnt vmcnt(7)
	v_pk_add_f32 v[116:117], v[90:91], 1.0 op_sel_hi:[1,0]
	s_waitcnt vmcnt(6)
	v_pk_add_f32 v[84:85], v[84:85], 1.0 op_sel_hi:[1,0]
	v_pk_add_f32 v[82:83], v[82:83], 1.0 op_sel_hi:[1,0]
	s_waitcnt vmcnt(5)
	v_pk_add_f32 v[88:89], v[88:89], 1.0 op_sel_hi:[1,0]
	v_pk_add_f32 v[86:87], v[86:87], 1.0 op_sel_hi:[1,0]
	v_pk_add_f32 v[92:93], v[92:93], 1.0 op_sel_hi:[1,0]
	s_nop 1
	v_add_f32_dpp v73, v73, v73 quad_perm:[1,0,3,2] row_mask:0xf bank_mask:0xf bound_ctrl:1
	s_nop 1
	v_add_f32_dpp v73, v73, v73 quad_perm:[2,3,0,1] row_mask:0xf bank_mask:0xf bound_ctrl:1
	s_nop 1
	v_add_f32_dpp v73, v73, v73 row_ror:4 row_mask:0xf bank_mask:0xf bound_ctrl:1
	s_nop 1
	v_add_f32_dpp v73, v73, v73 row_ror:8 row_mask:0xf bank_mask:0xf bound_ctrl:1
	s_nop 1
	v_mov_b32_e32 v98, v73
	s_nop 1
	v_permlane16_swap_b32_e32 v98, v73
	v_add_f32_e32 v73, v73, v98
	v_mov_b32_e32 v98, v73
	s_nop 1
	v_permlane32_swap_b32_e32 v98, v73
	v_add_f32_e32 v73, v73, v98
	s_waitcnt lgkmcnt(0)
	v_fmamk_f32 v73, v73, 0x3a800000, v183
	v_mul_f32_e32 v98, 0x4b800000, v73
	v_cmp_gt_f32_e32 vcc, s18, v73
	s_waitcnt vmcnt(4)
	v_pk_add_f32 v[118:119], v[96:97], 1.0 op_sel_hi:[1,0]
	v_cndmask_b32_e32 v73, v73, v98, vcc
	v_rsq_f32_e32 v73, v73
	v_pk_add_f32 v[94:95], v[94:95], 1.0 op_sel_hi:[1,0]
	v_mul_f32_e32 v90, 0x45800000, v73
	v_cndmask_b32_e32 v90, v73, v90, vcc
	v_pk_mul_f32 v[66:67], v[66:67], v[90:91] op_sel_hi:[1,0]
	v_pk_mul_f32 v[64:65], v[64:65], v[90:91] op_sel_hi:[1,0]
	v_pk_mul_f32 v[70:71], v[70:71], v[90:91] op_sel_hi:[1,0]
	v_pk_mul_f32 v[68:69], v[68:69], v[90:91] op_sel_hi:[1,0]
	v_pk_mul_f32 v[80:81], v[80:81], v[90:91] op_sel_hi:[1,0]
	v_pk_mul_f32 v[78:79], v[78:79], v[90:91] op_sel_hi:[1,0]
	v_pk_mul_f32 v[76:77], v[76:77], v[90:91] op_sel_hi:[1,0]
	v_pk_mul_f32 v[74:75], v[74:75], v[90:91] op_sel_hi:[1,0]
	v_pk_mul_f32 v[64:65], v[0:1], v[64:65]
	v_pk_mul_f32 v[66:67], v[2:3], v[66:67]
	v_pk_mul_f32 v[68:69], v[16:17], v[68:69]
	v_pk_mul_f32 v[70:71], v[18:19], v[70:71]
	v_pk_mul_f32 v[78:79], v[32:33], v[78:79]
	v_pk_mul_f32 v[80:81], v[34:35], v[80:81]
	v_pk_mul_f32 v[74:75], v[48:49], v[74:75]
	v_pk_mul_f32 v[76:77], v[50:51], v[76:77]
	s_waitcnt vmcnt(3)
	v_pk_fma_f32 v[98:99], v[84:85], v[66:67], v[102:103]
	v_pk_fma_f32 v[96:97], v[82:83], v[64:65], v[100:101]
	s_waitcnt vmcnt(2)
	v_pk_fma_f32 v[90:91], v[88:89], v[70:71], v[106:107]
	v_pk_fma_f32 v[88:89], v[86:87], v[68:69], v[104:105]
	s_waitcnt vmcnt(1)
	v_pk_fma_f32 v[70:71], v[92:93], v[80:81], v[110:111]
	v_pk_fma_f32 v[68:69], v[116:117], v[78:79], v[108:109]
	s_waitcnt vmcnt(0)
	v_pk_fma_f32 v[66:67], v[118:119], v[76:77], v[114:115]
	v_pk_fma_f32 v[64:65], v[94:95], v[74:75], v[112:113]
